# GEMM tile headers: LDS ring refilled without draining the previous tile's epilogue stores
# speedup vs baseline: 1.0045x; 1.0045x over previous
.LBB0_146:
	s_and_b32 s7, s4, 7
	v_lshl_add_u32 v0, s7, 8, v201
	v_ashrrev_i32_e32 v1, 31, v0
	v_lshlrev_b64 v[0:1], 11, v[0:1]
	s_and_b32 s7, s6, 0xffffff00
	v_lshl_add_u64 v[170:171], v[160:161], 0, v[0:1]
	v_add_u32_e32 v0, s7, v175
	s_and_b32 s7, s10, 7
	v_ashrrev_i32_e32 v1, 31, v0
	s_or_b32 s7, s7, s5
	v_lshlrev_b64 v[0:1], 11, v[0:1]
	s_lshl_b32 s7, s7, 8
	v_lshl_add_u64 v[172:173], v[168:169], 0, v[0:1]
	v_add_u32_e32 v0, s7, v175
	s_lshl_b32 s11, s10, 5
	v_ashrrev_i32_e32 v1, 31, v0
	s_and_b32 s11, s11, 0xffffff00
	v_add_u32_e32 v2, s11, v175
	v_lshlrev_b64 v[0:1], 11, v[0:1]
	s_waitcnt lgkmcnt(0)
	s_barrier
	v_ashrrev_i32_e32 v3, 31, v2
	v_lshl_add_u64 v[0:1], v[154:155], 0, v[0:1]
	v_readfirstlane_b32 s12, v180
	s_mov_b32 m0, s12
	s_nop 0
	global_load_lds_dwordx4 v[0:1], off
	v_lshlrev_b64 v[2:3], 11, v[2:3]
	v_lshl_add_u64 v[4:5], v[0:1], 0, s[34:35]
	s_add_i32 s13, s12, 0x2000
	s_mov_b32 m0, s13
	s_nop 0
	global_load_lds_dwordx4 v[4:5], off
	v_lshl_add_u64 v[2:3], v[156:157], 0, v[2:3]
	s_add_i32 s13, s12, 0x4000
	s_mov_b32 m0, s13
	s_nop 0
	global_load_lds_dwordx4 v[2:3], off
	v_lshl_add_u64 v[4:5], v[2:3], 0, s[34:35]
	s_add_i32 s13, s12, 0x6000
	s_mov_b32 m0, s13
	s_nop 0
	global_load_lds_dwordx4 v[4:5], off
	s_add_i32 s13, s12, 0x8000
	v_lshl_add_u64 v[4:5], v[0:1], 0, 64
	s_mov_b32 m0, s13
	s_nop 0
	global_load_lds_dwordx4 v[4:5], off
	s_mov_b64 s[14:15], 0x40040
	v_lshl_add_u64 v[4:5], v[0:1], 0, s[14:15]
	s_add_i32 s13, s12, 0xa000
	s_mov_b32 m0, s13
	s_nop 0
	global_load_lds_dwordx4 v[4:5], off
	v_lshl_add_u64 v[4:5], v[2:3], 0, 64
	s_add_i32 s13, s12, 0xc000
	s_mov_b32 m0, s13
	s_nop 0
	global_load_lds_dwordx4 v[4:5], off
	v_lshl_add_u64 v[4:5], v[2:3], 0, s[14:15]
	s_add_i32 s13, s12, 0xe000
	s_mov_b32 m0, s13
	s_nop 0
	global_load_lds_dwordx4 v[4:5], off
	s_mov_b64 s[14:15], 0x80
	s_add_i32 s13, s12, 0x10000
	v_lshl_add_u64 v[4:5], v[0:1], 0, s[14:15]
	s_mov_b32 m0, s13
	s_nop 0
	global_load_lds_dwordx4 v[4:5], off
	s_mov_b64 s[16:17], 0x40080
	v_lshl_add_u64 v[0:1], v[0:1], 0, s[16:17]
	s_add_i32 s13, s12, 0x12000
	s_mov_b32 m0, s13
	s_nop 0
	global_load_lds_dwordx4 v[0:1], off
	v_lshl_add_u64 v[0:1], v[2:3], 0, s[14:15]
	s_add_i32 s13, s12, 0x14000
	s_mov_b32 m0, s13
	s_nop 0
	global_load_lds_dwordx4 v[0:1], off
	v_lshl_add_u64 v[0:1], v[2:3], 0, s[16:17]
	s_add_i32 s12, s12, 0x16000
	s_mov_b32 m0, s12
	s_nop 0
	global_load_lds_dwordx4 v[0:1], off
	v_mov_b32_e32 v130, 0
	v_mov_b32_e32 v134, 0
	v_mov_b32_e32 v0, 0
	s_mov_b32 s12, 0x18000
	v_mov_b32_e32 v1, v0
	v_mov_b32_e32 v2, v0
	v_mov_b32_e32 v3, v0
	v_mov_b32_e32 v4, v0
	v_mov_b32_e32 v5, v0
	v_mov_b32_e32 v6, v0
	v_mov_b32_e32 v7, v0
	v_mov_b32_e32 v8, v0
	v_mov_b32_e32 v9, v0
	v_mov_b32_e32 v10, v0
	v_mov_b32_e32 v11, v0
	v_mov_b32_e32 v12, v0
	v_mov_b32_e32 v13, v0
	v_mov_b32_e32 v14, v0
	v_mov_b32_e32 v15, v0
	v_mov_b32_e32 v16, v0
	v_mov_b32_e32 v17, v0
	v_mov_b32_e32 v18, v0
	v_mov_b32_e32 v19, v0
	v_mov_b32_e32 v20, v0
	v_mov_b32_e32 v21, v0
	v_mov_b32_e32 v22, v0
	v_mov_b32_e32 v23, v0
	v_mov_b32_e32 v24, v0
	v_mov_b32_e32 v25, v0
	v_mov_b32_e32 v26, v0
	v_mov_b32_e32 v27, v0
	v_mov_b32_e32 v28, v0
	v_mov_b32_e32 v29, v0
	v_mov_b32_e32 v30, v0
	v_mov_b32_e32 v31, v0
	v_mov_b32_e32 v32, v0
	v_mov_b32_e32 v33, v0
	v_mov_b32_e32 v34, v0
	v_mov_b32_e32 v35, v0
	v_mov_b32_e32 v36, v0
	v_mov_b32_e32 v37, v0
	v_mov_b32_e32 v38, v0
	v_mov_b32_e32 v39, v0
	v_mov_b32_e32 v40, v0
	v_mov_b32_e32 v41, v0
	v_mov_b32_e32 v42, v0
	v_mov_b32_e32 v43, v0
	v_mov_b32_e32 v44, v0
	v_mov_b32_e32 v45, v0
	v_mov_b32_e32 v46, v0
	v_mov_b32_e32 v47, v0
	v_mov_b32_e32 v48, v0
	v_mov_b32_e32 v49, v0
	v_mov_b32_e32 v50, v0
	v_mov_b32_e32 v51, v0
	v_mov_b32_e32 v52, v0
	v_mov_b32_e32 v53, v0
	v_mov_b32_e32 v54, v0
	v_mov_b32_e32 v55, v0
	v_mov_b32_e32 v56, v0
	v_mov_b32_e32 v57, v0
	v_mov_b32_e32 v58, v0
	v_mov_b32_e32 v59, v0
	v_mov_b32_e32 v60, v0
	v_mov_b32_e32 v61, v0
	v_mov_b32_e32 v62, v0
	v_mov_b32_e32 v63, v0
	v_mov_b32_e32 v64, v0
	v_mov_b32_e32 v65, v0
	v_mov_b32_e32 v66, v0
	v_mov_b32_e32 v67, v0
	v_mov_b32_e32 v68, v0
	v_mov_b32_e32 v69, v0
	v_mov_b32_e32 v70, v0
	v_mov_b32_e32 v71, v0
	v_mov_b32_e32 v72, v0
	v_mov_b32_e32 v73, v0
	v_mov_b32_e32 v74, v0
	v_mov_b32_e32 v75, v0
	v_mov_b32_e32 v76, v0
	v_mov_b32_e32 v77, v0
	v_mov_b32_e32 v78, v0
	v_mov_b32_e32 v79, v0
	v_mov_b32_e32 v80, v0
	v_mov_b32_e32 v81, v0
	v_mov_b32_e32 v82, v0
	v_mov_b32_e32 v83, v0
	v_mov_b32_e32 v84, v0
	v_mov_b32_e32 v85, v0
	v_mov_b32_e32 v86, v0
	v_mov_b32_e32 v87, v0
	v_mov_b32_e32 v88, v0
	v_mov_b32_e32 v89, v0
	v_mov_b32_e32 v90, v0
	v_mov_b32_e32 v91, v0
	v_mov_b32_e32 v92, v0
	v_mov_b32_e32 v93, v0
	v_mov_b32_e32 v94, v0
	v_mov_b32_e32 v95, v0
	v_mov_b32_e32 v96, v0
	v_mov_b32_e32 v97, v0
	v_mov_b32_e32 v98, v0
	v_mov_b32_e32 v99, v0
	v_mov_b32_e32 v100, v0
	v_mov_b32_e32 v101, v0
	v_mov_b32_e32 v102, v0
	v_mov_b32_e32 v103, v0
	v_mov_b32_e32 v104, v0
	v_mov_b32_e32 v105, v0
	v_mov_b32_e32 v106, v0
	v_mov_b32_e32 v107, v0
	v_mov_b32_e32 v108, v0
	v_mov_b32_e32 v109, v0
	v_mov_b32_e32 v110, v0
	v_mov_b32_e32 v111, v0
	v_mov_b32_e32 v112, v0
	v_mov_b32_e32 v113, v0
	v_mov_b32_e32 v114, v0
	v_mov_b32_e32 v115, v0
	v_mov_b32_e32 v116, v0
	v_mov_b32_e32 v117, v0
	v_mov_b32_e32 v118, v0
	v_mov_b32_e32 v119, v0
	v_mov_b32_e32 v120, v0
	v_mov_b32_e32 v121, v0
	v_mov_b32_e32 v122, v0
	v_mov_b32_e32 v123, v0
	v_mov_b32_e32 v124, v0
	v_mov_b32_e32 v125, v0
	v_mov_b32_e32 v126, v0
	v_mov_b32_e32 v127, v0
	v_mov_b32_e32 v135, v134
	v_mov_b32_e32 v136, v134
	v_mov_b32_e32 v137, v134
	v_mov_b32_e32 v138, v134
	v_mov_b32_e32 v139, v134
	v_mov_b32_e32 v140, v134
	v_mov_b32_e32 v141, v134
	v_mov_b32_e32 v146, v134
	v_mov_b32_e32 v147, v134
	v_mov_b32_e32 v148, v134
	v_mov_b32_e32 v149, v134
	v_mov_b32_e32 v150, v134
	v_mov_b32_e32 v151, v134
	v_mov_b32_e32 v152, v134
	v_mov_b32_e32 v153, v134
	v_mov_b32_e32 v131, v130
	v_mov_b32_e32 v132, v130
	v_mov_b32_e32 v133, v130
	v_mov_b32_e32 v142, v130
	v_mov_b32_e32 v143, v130
	v_mov_b32_e32 v144, v130
	v_mov_b32_e32 v145, v130

.LBB0_262:
	s_and_b32 s5, s2, 7
	v_lshl_add_u32 v0, s5, 8, v201
	v_ashrrev_i32_e32 v1, 31, v0
	v_lshlrev_b64 v[0:1], 11, v[0:1]
	s_and_b32 s5, s4, 0xffffff00
	v_lshl_add_u64 v[170:171], v[160:161], 0, v[0:1]
	v_add_u32_e32 v0, s5, v175
	s_and_b32 s5, s6, 7
	v_ashrrev_i32_e32 v1, 31, v0
	s_or_b32 s5, s5, s3
	v_lshlrev_b64 v[0:1], 11, v[0:1]
	s_lshl_b32 s5, s5, 8
	v_lshl_add_u64 v[172:173], v[168:169], 0, v[0:1]
	v_add_u32_e32 v0, s5, v175
	s_lshl_b32 s7, s6, 5
	v_ashrrev_i32_e32 v1, 31, v0
	s_and_b32 s7, s7, 0xffffff00
	v_add_u32_e32 v2, s7, v175
	v_lshlrev_b64 v[0:1], 11, v[0:1]
	s_waitcnt lgkmcnt(0)
	s_barrier
	v_ashrrev_i32_e32 v3, 31, v2
	v_lshl_add_u64 v[0:1], v[154:155], 0, v[0:1]
	v_readfirstlane_b32 s10, v180
	s_mov_b32 m0, s10
	s_nop 0
	global_load_lds_dwordx4 v[0:1], off
	v_lshlrev_b64 v[2:3], 11, v[2:3]
	v_lshl_add_u64 v[4:5], v[0:1], 0, s[34:35]
	s_add_i32 s11, s10, 0x2000
	s_mov_b32 m0, s11
	s_nop 0
	global_load_lds_dwordx4 v[4:5], off
	v_lshl_add_u64 v[2:3], v[156:157], 0, v[2:3]
	s_add_i32 s11, s10, 0x4000
	s_mov_b32 m0, s11
	s_nop 0
	global_load_lds_dwordx4 v[2:3], off
	v_lshl_add_u64 v[4:5], v[2:3], 0, s[34:35]
	s_add_i32 s11, s10, 0x6000
	s_mov_b32 m0, s11
	s_nop 0
	global_load_lds_dwordx4 v[4:5], off
	s_add_i32 s11, s10, 0x8000
	v_lshl_add_u64 v[4:5], v[0:1], 0, 64
	s_mov_b32 m0, s11
	s_nop 0
	global_load_lds_dwordx4 v[4:5], off
	s_mov_b64 s[12:13], 0x40040
	v_lshl_add_u64 v[4:5], v[0:1], 0, s[12:13]
	s_add_i32 s11, s10, 0xa000
	s_mov_b32 m0, s11
	s_nop 0
	global_load_lds_dwordx4 v[4:5], off
	v_lshl_add_u64 v[4:5], v[2:3], 0, 64
	s_add_i32 s11, s10, 0xc000
	s_mov_b32 m0, s11
	s_nop 0
	global_load_lds_dwordx4 v[4:5], off
	v_lshl_add_u64 v[4:5], v[2:3], 0, s[12:13]
	s_add_i32 s11, s10, 0xe000
	s_mov_b32 m0, s11
	s_nop 0
	global_load_lds_dwordx4 v[4:5], off
	s_mov_b64 s[12:13], 0x80
	s_add_i32 s11, s10, 0x10000
	v_lshl_add_u64 v[4:5], v[0:1], 0, s[12:13]
	s_mov_b32 m0, s11
	s_nop 0
	global_load_lds_dwordx4 v[4:5], off
	s_mov_b64 s[14:15], 0x40080
	v_lshl_add_u64 v[0:1], v[0:1], 0, s[14:15]
	s_add_i32 s11, s10, 0x12000
	s_mov_b32 m0, s11
	s_nop 0
	global_load_lds_dwordx4 v[0:1], off
	v_lshl_add_u64 v[0:1], v[2:3], 0, s[12:13]
	s_add_i32 s11, s10, 0x14000
	s_mov_b32 m0, s11
	s_nop 0
	global_load_lds_dwordx4 v[0:1], off
	v_lshl_add_u64 v[0:1], v[2:3], 0, s[14:15]
	s_add_i32 s10, s10, 0x16000
	s_mov_b32 m0, s10
	s_nop 0
	global_load_lds_dwordx4 v[0:1], off
	v_mov_b32_e32 v130, 0
	v_mov_b32_e32 v134, 0
	v_mov_b32_e32 v0, 0
	s_mov_b32 s10, 0x18000
	v_mov_b32_e32 v1, v0
	v_mov_b32_e32 v2, v0
	v_mov_b32_e32 v3, v0
	v_mov_b32_e32 v4, v0
	v_mov_b32_e32 v5, v0
	v_mov_b32_e32 v6, v0
	v_mov_b32_e32 v7, v0
	v_mov_b32_e32 v8, v0
	v_mov_b32_e32 v9, v0
	v_mov_b32_e32 v10, v0
	v_mov_b32_e32 v11, v0
	v_mov_b32_e32 v12, v0
	v_mov_b32_e32 v13, v0
	v_mov_b32_e32 v14, v0
	v_mov_b32_e32 v15, v0
	v_mov_b32_e32 v16, v0
	v_mov_b32_e32 v17, v0
	v_mov_b32_e32 v18, v0
	v_mov_b32_e32 v19, v0
	v_mov_b32_e32 v20, v0
	v_mov_b32_e32 v21, v0
	v_mov_b32_e32 v22, v0
	v_mov_b32_e32 v23, v0
	v_mov_b32_e32 v24, v0
	v_mov_b32_e32 v25, v0
	v_mov_b32_e32 v26, v0
	v_mov_b32_e32 v27, v0
	v_mov_b32_e32 v28, v0
	v_mov_b32_e32 v29, v0
	v_mov_b32_e32 v30, v0
	v_mov_b32_e32 v31, v0
	v_mov_b32_e32 v32, v0
	v_mov_b32_e32 v33, v0
	v_mov_b32_e32 v34, v0
	v_mov_b32_e32 v35, v0
	v_mov_b32_e32 v36, v0
	v_mov_b32_e32 v37, v0
	v_mov_b32_e32 v38, v0
	v_mov_b32_e32 v39, v0
	v_mov_b32_e32 v40, v0
	v_mov_b32_e32 v41, v0
	v_mov_b32_e32 v42, v0
	v_mov_b32_e32 v43, v0
	v_mov_b32_e32 v44, v0
	v_mov_b32_e32 v45, v0
	v_mov_b32_e32 v46, v0
	v_mov_b32_e32 v47, v0
	v_mov_b32_e32 v48, v0
	v_mov_b32_e32 v49, v0
	v_mov_b32_e32 v50, v0
	v_mov_b32_e32 v51, v0
	v_mov_b32_e32 v52, v0
	v_mov_b32_e32 v53, v0
	v_mov_b32_e32 v54, v0
	v_mov_b32_e32 v55, v0
	v_mov_b32_e32 v56, v0
	v_mov_b32_e32 v57, v0
	v_mov_b32_e32 v58, v0
	v_mov_b32_e32 v59, v0
	v_mov_b32_e32 v60, v0
	v_mov_b32_e32 v61, v0
	v_mov_b32_e32 v62, v0
	v_mov_b32_e32 v63, v0
	v_mov_b32_e32 v64, v0
	v_mov_b32_e32 v65, v0
	v_mov_b32_e32 v66, v0
	v_mov_b32_e32 v67, v0
	v_mov_b32_e32 v68, v0
	v_mov_b32_e32 v69, v0
	v_mov_b32_e32 v70, v0
	v_mov_b32_e32 v71, v0
	v_mov_b32_e32 v72, v0
	v_mov_b32_e32 v73, v0
	v_mov_b32_e32 v74, v0
	v_mov_b32_e32 v75, v0
	v_mov_b32_e32 v76, v0
	v_mov_b32_e32 v77, v0
	v_mov_b32_e32 v78, v0
	v_mov_b32_e32 v79, v0
	v_mov_b32_e32 v80, v0
	v_mov_b32_e32 v81, v0
	v_mov_b32_e32 v82, v0
	v_mov_b32_e32 v83, v0
	v_mov_b32_e32 v84, v0
	v_mov_b32_e32 v85, v0
	v_mov_b32_e32 v86, v0
	v_mov_b32_e32 v87, v0
	v_mov_b32_e32 v88, v0
	v_mov_b32_e32 v89, v0
	v_mov_b32_e32 v90, v0
	v_mov_b32_e32 v91, v0
	v_mov_b32_e32 v92, v0
	v_mov_b32_e32 v93, v0
	v_mov_b32_e32 v94, v0
	v_mov_b32_e32 v95, v0
	v_mov_b32_e32 v96, v0
	v_mov_b32_e32 v97, v0
	v_mov_b32_e32 v98, v0
	v_mov_b32_e32 v99, v0
	v_mov_b32_e32 v100, v0
	v_mov_b32_e32 v101, v0
	v_mov_b32_e32 v102, v0
	v_mov_b32_e32 v103, v0
	v_mov_b32_e32 v104, v0
	v_mov_b32_e32 v105, v0
	v_mov_b32_e32 v106, v0
	v_mov_b32_e32 v107, v0
	v_mov_b32_e32 v108, v0
	v_mov_b32_e32 v109, v0
	v_mov_b32_e32 v110, v0
	v_mov_b32_e32 v111, v0
	v_mov_b32_e32 v112, v0
	v_mov_b32_e32 v113, v0
	v_mov_b32_e32 v114, v0
	v_mov_b32_e32 v115, v0
	v_mov_b32_e32 v116, v0
	v_mov_b32_e32 v117, v0
	v_mov_b32_e32 v118, v0
	v_mov_b32_e32 v119, v0
	v_mov_b32_e32 v120, v0
	v_mov_b32_e32 v121, v0
	v_mov_b32_e32 v122, v0
	v_mov_b32_e32 v123, v0
	v_mov_b32_e32 v124, v0
	v_mov_b32_e32 v125, v0
	v_mov_b32_e32 v126, v0
	v_mov_b32_e32 v127, v0
	v_mov_b32_e32 v135, v134
	v_mov_b32_e32 v136, v134
	v_mov_b32_e32 v137, v134
	v_mov_b32_e32 v138, v134
	v_mov_b32_e32 v139, v134
	v_mov_b32_e32 v140, v134
	v_mov_b32_e32 v141, v134
	v_mov_b32_e32 v146, v134
	v_mov_b32_e32 v147, v134
	v_mov_b32_e32 v148, v134
	v_mov_b32_e32 v149, v134
	v_mov_b32_e32 v150, v134
	v_mov_b32_e32 v151, v134
	v_mov_b32_e32 v152, v134
	v_mov_b32_e32 v153, v134
	v_mov_b32_e32 v131, v130
	v_mov_b32_e32 v132, v130
	v_mov_b32_e32 v133, v130
	v_mov_b32_e32 v142, v130
	v_mov_b32_e32 v143, v130
	v_mov_b32_e32 v144, v130
	v_mov_b32_e32 v145, v130

.LBB0_329:
	s_and_b32 s0, s31, 7
	v_lshl_add_u32 v0, s0, 8, v189
	v_ashrrev_i32_e32 v1, 31, v0
	v_lshlrev_b64 v[0:1], 11, v[0:1]
	s_and_b32 s0, s35, 0xffffff00
	v_lshl_add_u64 v[172:173], v[168:169], 0, v[0:1]
	v_add_u32_e32 v0, s0, v177
	s_and_b32 s0, s30, 7
	v_ashrrev_i32_e32 v1, 31, v0
	s_or_b32 s0, s0, s34
	v_lshlrev_b64 v[0:1], 11, v[0:1]
	s_lshl_b32 s0, s0, 8
	v_lshl_add_u64 v[174:175], v[170:171], 0, v[0:1]
	v_add_u32_e32 v0, s0, v177
	s_lshl_b32 s1, s30, 5
	v_ashrrev_i32_e32 v1, 31, v0
	s_and_b32 s1, s1, 0xffffff00
	v_lshlrev_b64 v[0:1], 11, v[0:1]
	v_add_u32_e32 v2, s1, v177
	s_waitcnt lgkmcnt(0)
	s_barrier
	v_ashrrev_i32_e32 v3, 31, v2
	v_lshl_add_u64 v[0:1], v[158:159], 0, v[0:1]
	v_readfirstlane_b32 s2, v182
	s_mov_b32 m0, s2
	s_nop 0
	global_load_lds_dwordx4 v[0:1], off
	s_mov_b64 s[26:27], 0x40000
	v_lshlrev_b64 v[2:3], 11, v[2:3]
	v_lshl_add_u64 v[4:5], v[0:1], 0, s[26:27]
	s_add_i32 s3, s2, 0x2000
	s_mov_b32 m0, s3
	s_nop 0
	global_load_lds_dwordx4 v[4:5], off
	v_lshl_add_u64 v[2:3], v[160:161], 0, v[2:3]
	s_add_i32 s3, s2, 0x4000
	s_mov_b32 m0, s3
	s_nop 0
	global_load_lds_dwordx4 v[2:3], off
	v_lshl_add_u64 v[4:5], v[2:3], 0, s[26:27]
	s_add_i32 s3, s2, 0x6000
	s_mov_b32 m0, s3
	s_nop 0
	global_load_lds_dwordx4 v[4:5], off
	s_add_i32 s3, s2, 0x8000
	v_lshl_add_u64 v[4:5], v[0:1], 0, 64
	s_mov_b32 m0, s3
	s_nop 0
	global_load_lds_dwordx4 v[4:5], off
	s_mov_b64 s[24:25], 0x40040
	v_lshl_add_u64 v[4:5], v[0:1], 0, s[24:25]
	s_add_i32 s3, s2, 0xa000
	s_mov_b32 m0, s3
	s_nop 0
	global_load_lds_dwordx4 v[4:5], off
	v_lshl_add_u64 v[4:5], v[2:3], 0, 64
	s_add_i32 s3, s2, 0xc000
	s_mov_b32 m0, s3
	s_nop 0
	global_load_lds_dwordx4 v[4:5], off
	v_lshl_add_u64 v[4:5], v[2:3], 0, s[24:25]
	s_add_i32 s3, s2, 0xe000
	s_mov_b32 m0, s3
	s_nop 0
	global_load_lds_dwordx4 v[4:5], off
	s_mov_b64 s[24:25], 0x80
	s_add_i32 s3, s2, 0x10000
	v_lshl_add_u64 v[4:5], v[0:1], 0, s[24:25]
	s_mov_b32 m0, s3
	s_nop 0
	global_load_lds_dwordx4 v[4:5], off
	s_mov_b64 s[28:29], 0x40080
	v_lshl_add_u64 v[0:1], v[0:1], 0, s[28:29]
	s_add_i32 s3, s2, 0x12000
	s_mov_b32 m0, s3
	s_nop 0
	global_load_lds_dwordx4 v[0:1], off
	v_lshl_add_u64 v[0:1], v[2:3], 0, s[24:25]
	s_add_i32 s3, s2, 0x14000
	s_mov_b32 m0, s3
	s_nop 0
	global_load_lds_dwordx4 v[0:1], off
	v_lshl_add_u64 v[0:1], v[2:3], 0, s[28:29]
	s_add_i32 s2, s2, 0x16000
	s_mov_b32 m0, s2
	s_nop 0
	global_load_lds_dwordx4 v[0:1], off
	v_mov_b32_e32 v130, 0
	v_mov_b32_e32 v134, 0
	v_mov_b32_e32 v0, 0
	s_mov_b32 s2, 0x18000
	v_mov_b32_e32 v1, v0
	v_mov_b32_e32 v2, v0
	v_mov_b32_e32 v3, v0
	v_mov_b32_e32 v4, v0
	v_mov_b32_e32 v5, v0
	v_mov_b32_e32 v6, v0
	v_mov_b32_e32 v7, v0
	v_mov_b32_e32 v8, v0
	v_mov_b32_e32 v9, v0
	v_mov_b32_e32 v10, v0
	v_mov_b32_e32 v11, v0
	v_mov_b32_e32 v12, v0
	v_mov_b32_e32 v13, v0
	v_mov_b32_e32 v14, v0
	v_mov_b32_e32 v15, v0
	v_mov_b32_e32 v16, v0
	v_mov_b32_e32 v17, v0
	v_mov_b32_e32 v18, v0
	v_mov_b32_e32 v19, v0
	v_mov_b32_e32 v20, v0
	v_mov_b32_e32 v21, v0
	v_mov_b32_e32 v22, v0
	v_mov_b32_e32 v23, v0
	v_mov_b32_e32 v24, v0
	v_mov_b32_e32 v25, v0
	v_mov_b32_e32 v26, v0
	v_mov_b32_e32 v27, v0
	v_mov_b32_e32 v28, v0
	v_mov_b32_e32 v29, v0
	v_mov_b32_e32 v30, v0
	v_mov_b32_e32 v31, v0
	v_mov_b32_e32 v32, v0
	v_mov_b32_e32 v33, v0
	v_mov_b32_e32 v34, v0
	v_mov_b32_e32 v35, v0
	v_mov_b32_e32 v36, v0
	v_mov_b32_e32 v37, v0
	v_mov_b32_e32 v38, v0
	v_mov_b32_e32 v39, v0
	v_mov_b32_e32 v40, v0
	v_mov_b32_e32 v41, v0
	v_mov_b32_e32 v42, v0
	v_mov_b32_e32 v43, v0
	v_mov_b32_e32 v44, v0
	v_mov_b32_e32 v45, v0
	v_mov_b32_e32 v46, v0
	v_mov_b32_e32 v47, v0
	v_mov_b32_e32 v48, v0
	v_mov_b32_e32 v49, v0
	v_mov_b32_e32 v50, v0
	v_mov_b32_e32 v51, v0
	v_mov_b32_e32 v52, v0
	v_mov_b32_e32 v53, v0
	v_mov_b32_e32 v54, v0
	v_mov_b32_e32 v55, v0
	v_mov_b32_e32 v56, v0
	v_mov_b32_e32 v57, v0
	v_mov_b32_e32 v58, v0
	v_mov_b32_e32 v59, v0
	v_mov_b32_e32 v60, v0
	v_mov_b32_e32 v61, v0
	v_mov_b32_e32 v62, v0
	v_mov_b32_e32 v63, v0
	v_mov_b32_e32 v64, v0
	v_mov_b32_e32 v65, v0
	v_mov_b32_e32 v66, v0
	v_mov_b32_e32 v67, v0
	v_mov_b32_e32 v68, v0
	v_mov_b32_e32 v69, v0
	v_mov_b32_e32 v70, v0
	v_mov_b32_e32 v71, v0
	v_mov_b32_e32 v72, v0
	v_mov_b32_e32 v73, v0
	v_mov_b32_e32 v74, v0
	v_mov_b32_e32 v75, v0
	v_mov_b32_e32 v76, v0
	v_mov_b32_e32 v77, v0
	v_mov_b32_e32 v78, v0
	v_mov_b32_e32 v79, v0
	v_mov_b32_e32 v80, v0
	v_mov_b32_e32 v81, v0
	v_mov_b32_e32 v82, v0
	v_mov_b32_e32 v83, v0
	v_mov_b32_e32 v84, v0
	v_mov_b32_e32 v85, v0
	v_mov_b32_e32 v86, v0
	v_mov_b32_e32 v87, v0
	v_mov_b32_e32 v88, v0
	v_mov_b32_e32 v89, v0
	v_mov_b32_e32 v90, v0
	v_mov_b32_e32 v91, v0
	v_mov_b32_e32 v92, v0
	v_mov_b32_e32 v93, v0
	v_mov_b32_e32 v94, v0
	v_mov_b32_e32 v95, v0
	v_mov_b32_e32 v96, v0
	v_mov_b32_e32 v97, v0
	v_mov_b32_e32 v98, v0
	v_mov_b32_e32 v99, v0
	v_mov_b32_e32 v100, v0
	v_mov_b32_e32 v101, v0
	v_mov_b32_e32 v102, v0
	v_mov_b32_e32 v103, v0
	v_mov_b32_e32 v104, v0
	v_mov_b32_e32 v105, v0
	v_mov_b32_e32 v106, v0
	v_mov_b32_e32 v107, v0
	v_mov_b32_e32 v108, v0
	v_mov_b32_e32 v109, v0
	v_mov_b32_e32 v110, v0
	v_mov_b32_e32 v111, v0
	v_mov_b32_e32 v112, v0
	v_mov_b32_e32 v113, v0
	v_mov_b32_e32 v114, v0
	v_mov_b32_e32 v115, v0
	v_mov_b32_e32 v116, v0
	v_mov_b32_e32 v117, v0
	v_mov_b32_e32 v118, v0
	v_mov_b32_e32 v119, v0
	v_mov_b32_e32 v120, v0
	v_mov_b32_e32 v121, v0
	v_mov_b32_e32 v122, v0
	v_mov_b32_e32 v123, v0
	v_mov_b32_e32 v124, v0
	v_mov_b32_e32 v125, v0
	v_mov_b32_e32 v126, v0
	v_mov_b32_e32 v127, v0
	v_mov_b32_e32 v135, v134
	v_mov_b32_e32 v136, v134
	v_mov_b32_e32 v137, v134
	v_mov_b32_e32 v138, v134
	v_mov_b32_e32 v139, v134
	v_mov_b32_e32 v140, v134
	v_mov_b32_e32 v141, v134
	v_mov_b32_e32 v146, v134
	v_mov_b32_e32 v147, v134
	v_mov_b32_e32 v148, v134
	v_mov_b32_e32 v149, v134
	v_mov_b32_e32 v150, v134
	v_mov_b32_e32 v151, v134
	v_mov_b32_e32 v152, v134
	v_mov_b32_e32 v153, v134
	v_mov_b32_e32 v131, v130
	v_mov_b32_e32 v132, v130
	v_mov_b32_e32 v133, v130
	v_mov_b32_e32 v142, v130
	v_mov_b32_e32 v143, v130
	v_mov_b32_e32 v144, v130
	v_mov_b32_e32 v145, v130

.LBB0_1101:
	s_and_b32 s3, s0, 7
	v_lshl_add_u32 v0, s3, 8, v201
	v_ashrrev_i32_e32 v1, 31, v0
	v_lshlrev_b64 v[0:1], 11, v[0:1]
	s_and_b32 s3, s2, 0xffffff00
	v_lshl_add_u64 v[170:171], v[160:161], 0, v[0:1]
	v_add_u32_e32 v0, s3, v175
	s_and_b32 s3, s4, 7
	v_ashrrev_i32_e32 v1, 31, v0
	s_or_b32 s3, s3, s1
	v_lshlrev_b64 v[0:1], 11, v[0:1]
	s_lshl_b32 s3, s3, 8
	v_lshl_add_u64 v[172:173], v[168:169], 0, v[0:1]
	v_add_u32_e32 v0, s3, v175
	s_lshl_b32 s5, s4, 5
	v_ashrrev_i32_e32 v1, 31, v0
	s_and_b32 s5, s5, 0xffffff00
	v_add_u32_e32 v2, s5, v175
	v_lshlrev_b64 v[0:1], 11, v[0:1]
	s_waitcnt lgkmcnt(0)
	s_barrier
	v_ashrrev_i32_e32 v3, 31, v2
	v_lshl_add_u64 v[0:1], v[154:155], 0, v[0:1]
	v_readfirstlane_b32 s6, v180
	s_mov_b32 m0, s6
	s_nop 0
	global_load_lds_dwordx4 v[0:1], off
	v_lshlrev_b64 v[2:3], 11, v[2:3]
	v_lshl_add_u64 v[4:5], v[0:1], 0, s[34:35]
	s_add_i32 s7, s6, 0x2000
	s_mov_b32 m0, s7
	s_nop 0
	global_load_lds_dwordx4 v[4:5], off
	v_lshl_add_u64 v[2:3], v[156:157], 0, v[2:3]
	s_add_i32 s7, s6, 0x4000
	s_mov_b32 m0, s7
	s_nop 0
	global_load_lds_dwordx4 v[2:3], off
	v_lshl_add_u64 v[4:5], v[2:3], 0, s[34:35]
	s_add_i32 s7, s6, 0x6000
	s_mov_b32 m0, s7
	s_nop 0
	global_load_lds_dwordx4 v[4:5], off
	s_add_i32 s7, s6, 0x8000
	v_lshl_add_u64 v[4:5], v[0:1], 0, 64
	s_mov_b32 m0, s7
	s_nop 0
	global_load_lds_dwordx4 v[4:5], off
	s_mov_b64 s[10:11], 0x40040
	v_lshl_add_u64 v[4:5], v[0:1], 0, s[10:11]
	s_add_i32 s7, s6, 0xa000
	s_mov_b32 m0, s7
	s_nop 0
	global_load_lds_dwordx4 v[4:5], off
	v_lshl_add_u64 v[4:5], v[2:3], 0, 64
	s_add_i32 s7, s6, 0xc000
	s_mov_b32 m0, s7
	s_nop 0
	global_load_lds_dwordx4 v[4:5], off
	v_lshl_add_u64 v[4:5], v[2:3], 0, s[10:11]
	s_add_i32 s7, s6, 0xe000
	s_mov_b32 m0, s7
	s_nop 0
	global_load_lds_dwordx4 v[4:5], off
	s_mov_b64 s[10:11], 0x80
	s_add_i32 s7, s6, 0x10000
	v_lshl_add_u64 v[4:5], v[0:1], 0, s[10:11]
	s_mov_b32 m0, s7
	s_nop 0
	global_load_lds_dwordx4 v[4:5], off
	s_mov_b64 s[12:13], 0x40080
	v_lshl_add_u64 v[0:1], v[0:1], 0, s[12:13]
	s_add_i32 s7, s6, 0x12000
	s_mov_b32 m0, s7
	s_nop 0
	global_load_lds_dwordx4 v[0:1], off
	v_lshl_add_u64 v[0:1], v[2:3], 0, s[10:11]
	s_add_i32 s7, s6, 0x14000
	s_mov_b32 m0, s7
	s_nop 0
	global_load_lds_dwordx4 v[0:1], off
	v_lshl_add_u64 v[0:1], v[2:3], 0, s[12:13]
	s_add_i32 s6, s6, 0x16000
	s_mov_b32 m0, s6
	s_nop 0
	global_load_lds_dwordx4 v[0:1], off
	v_mov_b32_e32 v130, 0
	v_mov_b32_e32 v134, 0
	v_mov_b32_e32 v0, 0
	s_mov_b32 s6, 0x18000
	v_mov_b32_e32 v1, v0
	v_mov_b32_e32 v2, v0
	v_mov_b32_e32 v3, v0
	v_mov_b32_e32 v4, v0
	v_mov_b32_e32 v5, v0
	v_mov_b32_e32 v6, v0
	v_mov_b32_e32 v7, v0
	v_mov_b32_e32 v8, v0
	v_mov_b32_e32 v9, v0
	v_mov_b32_e32 v10, v0
	v_mov_b32_e32 v11, v0
	v_mov_b32_e32 v12, v0
	v_mov_b32_e32 v13, v0
	v_mov_b32_e32 v14, v0
	v_mov_b32_e32 v15, v0
	v_mov_b32_e32 v16, v0
	v_mov_b32_e32 v17, v0
	v_mov_b32_e32 v18, v0
	v_mov_b32_e32 v19, v0
	v_mov_b32_e32 v20, v0
	v_mov_b32_e32 v21, v0
	v_mov_b32_e32 v22, v0
	v_mov_b32_e32 v23, v0
	v_mov_b32_e32 v24, v0
	v_mov_b32_e32 v25, v0
	v_mov_b32_e32 v26, v0
	v_mov_b32_e32 v27, v0
	v_mov_b32_e32 v28, v0
	v_mov_b32_e32 v29, v0
	v_mov_b32_e32 v30, v0
	v_mov_b32_e32 v31, v0
	v_mov_b32_e32 v32, v0
	v_mov_b32_e32 v33, v0
	v_mov_b32_e32 v34, v0
	v_mov_b32_e32 v35, v0
	v_mov_b32_e32 v36, v0
	v_mov_b32_e32 v37, v0
	v_mov_b32_e32 v38, v0
	v_mov_b32_e32 v39, v0
	v_mov_b32_e32 v40, v0
	v_mov_b32_e32 v41, v0
	v_mov_b32_e32 v42, v0
	v_mov_b32_e32 v43, v0
	v_mov_b32_e32 v44, v0
	v_mov_b32_e32 v45, v0
	v_mov_b32_e32 v46, v0
	v_mov_b32_e32 v47, v0
	v_mov_b32_e32 v48, v0
	v_mov_b32_e32 v49, v0
	v_mov_b32_e32 v50, v0
	v_mov_b32_e32 v51, v0
	v_mov_b32_e32 v52, v0
	v_mov_b32_e32 v53, v0
	v_mov_b32_e32 v54, v0
	v_mov_b32_e32 v55, v0
	v_mov_b32_e32 v56, v0
	v_mov_b32_e32 v57, v0
	v_mov_b32_e32 v58, v0
	v_mov_b32_e32 v59, v0
	v_mov_b32_e32 v60, v0
	v_mov_b32_e32 v61, v0
	v_mov_b32_e32 v62, v0
	v_mov_b32_e32 v63, v0
	v_mov_b32_e32 v64, v0
	v_mov_b32_e32 v65, v0
	v_mov_b32_e32 v66, v0
	v_mov_b32_e32 v67, v0
	v_mov_b32_e32 v68, v0
	v_mov_b32_e32 v69, v0
	v_mov_b32_e32 v70, v0
	v_mov_b32_e32 v71, v0
	v_mov_b32_e32 v72, v0
	v_mov_b32_e32 v73, v0
	v_mov_b32_e32 v74, v0
	v_mov_b32_e32 v75, v0
	v_mov_b32_e32 v76, v0
	v_mov_b32_e32 v77, v0
	v_mov_b32_e32 v78, v0
	v_mov_b32_e32 v79, v0
	v_mov_b32_e32 v80, v0
	v_mov_b32_e32 v81, v0
	v_mov_b32_e32 v82, v0
	v_mov_b32_e32 v83, v0
	v_mov_b32_e32 v84, v0
	v_mov_b32_e32 v85, v0
	v_mov_b32_e32 v86, v0
	v_mov_b32_e32 v87, v0
	v_mov_b32_e32 v88, v0
	v_mov_b32_e32 v89, v0
	v_mov_b32_e32 v90, v0
	v_mov_b32_e32 v91, v0
	v_mov_b32_e32 v92, v0
	v_mov_b32_e32 v93, v0
	v_mov_b32_e32 v94, v0
	v_mov_b32_e32 v95, v0
	v_mov_b32_e32 v96, v0
	v_mov_b32_e32 v97, v0
	v_mov_b32_e32 v98, v0
	v_mov_b32_e32 v99, v0
	v_mov_b32_e32 v100, v0
	v_mov_b32_e32 v101, v0
	v_mov_b32_e32 v102, v0
	v_mov_b32_e32 v103, v0
	v_mov_b32_e32 v104, v0
	v_mov_b32_e32 v105, v0
	v_mov_b32_e32 v106, v0
	v_mov_b32_e32 v107, v0
	v_mov_b32_e32 v108, v0
	v_mov_b32_e32 v109, v0
	v_mov_b32_e32 v110, v0
	v_mov_b32_e32 v111, v0
	v_mov_b32_e32 v112, v0
	v_mov_b32_e32 v113, v0
	v_mov_b32_e32 v114, v0
	v_mov_b32_e32 v115, v0
	v_mov_b32_e32 v116, v0
	v_mov_b32_e32 v117, v0
	v_mov_b32_e32 v118, v0
	v_mov_b32_e32 v119, v0
	v_mov_b32_e32 v120, v0
	v_mov_b32_e32 v121, v0
	v_mov_b32_e32 v122, v0
	v_mov_b32_e32 v123, v0
	v_mov_b32_e32 v124, v0
	v_mov_b32_e32 v125, v0
	v_mov_b32_e32 v126, v0
	v_mov_b32_e32 v127, v0
	v_mov_b32_e32 v135, v134
	v_mov_b32_e32 v136, v134
	v_mov_b32_e32 v137, v134
	v_mov_b32_e32 v138, v134
	v_mov_b32_e32 v139, v134
	v_mov_b32_e32 v140, v134
	v_mov_b32_e32 v141, v134
	v_mov_b32_e32 v146, v134
	v_mov_b32_e32 v147, v134
	v_mov_b32_e32 v148, v134
	v_mov_b32_e32 v149, v134
	v_mov_b32_e32 v150, v134
	v_mov_b32_e32 v151, v134
	v_mov_b32_e32 v152, v134
	v_mov_b32_e32 v153, v134
	v_mov_b32_e32 v131, v130
	v_mov_b32_e32 v132, v130
	v_mov_b32_e32 v133, v130
	v_mov_b32_e32 v142, v130
	v_mov_b32_e32 v143, v130
	v_mov_b32_e32 v144, v130
	v_mov_b32_e32 v145, v130

.LBB0_1160:
	s_and_b32 s0, s31, 7
	s_nop 0
	v_lshl_add_u32 v0, s0, 8, v238
	v_ashrrev_i32_e32 v1, 31, v0
	v_lshlrev_b64 v[0:1], 11, v[0:1]
	s_and_b32 s0, s35, 0xffffff00
	v_lshl_add_u64 v[172:173], v[168:169], 0, v[0:1]
	v_add_u32_e32 v0, s0, v198
	s_and_b32 s0, s30, 7
	v_ashrrev_i32_e32 v1, 31, v0
	s_or_b32 s0, s0, s34
	v_lshlrev_b64 v[0:1], 11, v[0:1]
	s_lshl_b32 s0, s0, 8
	v_lshl_add_u64 v[174:175], v[170:171], 0, v[0:1]
	v_add_u32_e32 v0, s0, v198
	s_lshl_b32 s24, s30, 5
	v_ashrrev_i32_e32 v1, 31, v0
	s_and_b32 s1, s24, 0xffffff00
	v_lshlrev_b64 v[0:1], 11, v[0:1]
	v_add_u32_e32 v2, s1, v198
	s_waitcnt lgkmcnt(0)
	s_barrier
	v_ashrrev_i32_e32 v3, 31, v2
	v_lshl_add_u64 v[0:1], v[154:155], 0, v[0:1]
	v_readfirstlane_b32 s20, v203
	s_mov_b32 m0, s20
	s_nop 0
	global_load_lds_dwordx4 v[0:1], off
	s_mov_b64 s[26:27], 0x40000
	v_lshlrev_b64 v[2:3], 11, v[2:3]
	v_lshl_add_u64 v[4:5], v[0:1], 0, s[26:27]
	s_add_i32 s21, s20, 0x2000
	s_mov_b32 m0, s21
	s_nop 0
	global_load_lds_dwordx4 v[4:5], off
	v_lshl_add_u64 v[2:3], v[156:157], 0, v[2:3]
	s_add_i32 s21, s20, 0x4000
	s_mov_b32 m0, s21
	s_nop 0
	global_load_lds_dwordx4 v[2:3], off
	v_lshl_add_u64 v[4:5], v[2:3], 0, s[26:27]
	s_add_i32 s21, s20, 0x6000
	s_mov_b32 m0, s21
	s_nop 0
	global_load_lds_dwordx4 v[4:5], off
	s_add_i32 s21, s20, 0x8000
	v_lshl_add_u64 v[4:5], v[0:1], 0, 64
	s_mov_b32 m0, s21
	s_nop 0
	global_load_lds_dwordx4 v[4:5], off
	s_mov_b64 s[22:23], 0x40040
	v_lshl_add_u64 v[4:5], v[0:1], 0, s[22:23]
	s_add_i32 s21, s20, 0xa000
	s_mov_b32 m0, s21
	s_nop 0
	global_load_lds_dwordx4 v[4:5], off
	v_lshl_add_u64 v[4:5], v[2:3], 0, 64
	s_add_i32 s21, s20, 0xc000
	s_mov_b32 m0, s21
	s_nop 0
	global_load_lds_dwordx4 v[4:5], off
	v_lshl_add_u64 v[4:5], v[2:3], 0, s[22:23]
	s_add_i32 s21, s20, 0xe000
	s_mov_b32 m0, s21
	s_nop 0
	global_load_lds_dwordx4 v[4:5], off
	s_mov_b64 s[22:23], 0x80
	s_add_i32 s21, s20, 0x10000
	v_lshl_add_u64 v[4:5], v[0:1], 0, s[22:23]
	s_mov_b32 m0, s21
	s_nop 0
	global_load_lds_dwordx4 v[4:5], off
	s_mov_b64 s[28:29], 0x40080
	v_lshl_add_u64 v[0:1], v[0:1], 0, s[28:29]
	s_add_i32 s21, s20, 0x12000
	s_mov_b32 m0, s21
	s_nop 0
	global_load_lds_dwordx4 v[0:1], off
	v_lshl_add_u64 v[0:1], v[2:3], 0, s[22:23]
	s_add_i32 s21, s20, 0x14000
	s_mov_b32 m0, s21
	s_nop 0
	global_load_lds_dwordx4 v[0:1], off
	v_lshl_add_u64 v[0:1], v[2:3], 0, s[28:29]
	s_add_i32 s20, s20, 0x16000
	s_mov_b32 m0, s20
	s_nop 0
	global_load_lds_dwordx4 v[0:1], off
	v_mov_b32_e32 v130, 0
	v_mov_b32_e32 v134, 0
	v_mov_b32_e32 v0, 0
	s_mov_b32 s20, 0x18000
	v_mov_b32_e32 v1, v0
	v_mov_b32_e32 v2, v0
	v_mov_b32_e32 v3, v0
	v_mov_b32_e32 v4, v0
	v_mov_b32_e32 v5, v0
	v_mov_b32_e32 v6, v0
	v_mov_b32_e32 v7, v0
	v_mov_b32_e32 v8, v0
	v_mov_b32_e32 v9, v0
	v_mov_b32_e32 v10, v0
	v_mov_b32_e32 v11, v0
	v_mov_b32_e32 v12, v0
	v_mov_b32_e32 v13, v0
	v_mov_b32_e32 v14, v0
	v_mov_b32_e32 v15, v0
	v_mov_b32_e32 v16, v0
	v_mov_b32_e32 v17, v0
	v_mov_b32_e32 v18, v0
	v_mov_b32_e32 v19, v0
	v_mov_b32_e32 v20, v0
	v_mov_b32_e32 v21, v0
	v_mov_b32_e32 v22, v0
	v_mov_b32_e32 v23, v0
	v_mov_b32_e32 v24, v0
	v_mov_b32_e32 v25, v0
	v_mov_b32_e32 v26, v0
	v_mov_b32_e32 v27, v0
	v_mov_b32_e32 v28, v0
	v_mov_b32_e32 v29, v0
	v_mov_b32_e32 v30, v0
	v_mov_b32_e32 v31, v0
	v_mov_b32_e32 v32, v0
	v_mov_b32_e32 v33, v0
	v_mov_b32_e32 v34, v0
	v_mov_b32_e32 v35, v0
	v_mov_b32_e32 v36, v0
	v_mov_b32_e32 v37, v0
	v_mov_b32_e32 v38, v0
	v_mov_b32_e32 v39, v0
	v_mov_b32_e32 v40, v0
	v_mov_b32_e32 v41, v0
	v_mov_b32_e32 v42, v0
	v_mov_b32_e32 v43, v0
	v_mov_b32_e32 v44, v0
	v_mov_b32_e32 v45, v0
	v_mov_b32_e32 v46, v0
	v_mov_b32_e32 v47, v0
	v_mov_b32_e32 v48, v0
	v_mov_b32_e32 v49, v0
	v_mov_b32_e32 v50, v0
	v_mov_b32_e32 v51, v0
	v_mov_b32_e32 v52, v0
	v_mov_b32_e32 v53, v0
	v_mov_b32_e32 v54, v0
	v_mov_b32_e32 v55, v0
	v_mov_b32_e32 v56, v0
	v_mov_b32_e32 v57, v0
	v_mov_b32_e32 v58, v0
	v_mov_b32_e32 v59, v0
	v_mov_b32_e32 v60, v0
	v_mov_b32_e32 v61, v0
	v_mov_b32_e32 v62, v0
	v_mov_b32_e32 v63, v0
	v_mov_b32_e32 v64, v0
	v_mov_b32_e32 v65, v0
	v_mov_b32_e32 v66, v0
	v_mov_b32_e32 v67, v0
	v_mov_b32_e32 v68, v0
	v_mov_b32_e32 v69, v0
	v_mov_b32_e32 v70, v0
	v_mov_b32_e32 v71, v0
	v_mov_b32_e32 v72, v0
	v_mov_b32_e32 v73, v0
	v_mov_b32_e32 v74, v0
	v_mov_b32_e32 v75, v0
	v_mov_b32_e32 v76, v0
	v_mov_b32_e32 v77, v0
	v_mov_b32_e32 v78, v0
	v_mov_b32_e32 v79, v0
	v_mov_b32_e32 v80, v0
	v_mov_b32_e32 v81, v0
	v_mov_b32_e32 v82, v0
	v_mov_b32_e32 v83, v0
	v_mov_b32_e32 v84, v0
	v_mov_b32_e32 v85, v0
	v_mov_b32_e32 v86, v0
	v_mov_b32_e32 v87, v0
	v_mov_b32_e32 v88, v0
	v_mov_b32_e32 v89, v0
	v_mov_b32_e32 v90, v0
	v_mov_b32_e32 v91, v0
	v_mov_b32_e32 v92, v0
	v_mov_b32_e32 v93, v0
	v_mov_b32_e32 v94, v0
	v_mov_b32_e32 v95, v0
	v_mov_b32_e32 v96, v0
	v_mov_b32_e32 v97, v0
	v_mov_b32_e32 v98, v0
	v_mov_b32_e32 v99, v0
	v_mov_b32_e32 v100, v0
	v_mov_b32_e32 v101, v0
	v_mov_b32_e32 v102, v0
	v_mov_b32_e32 v103, v0
	v_mov_b32_e32 v104, v0
	v_mov_b32_e32 v105, v0
	v_mov_b32_e32 v106, v0
	v_mov_b32_e32 v107, v0
	v_mov_b32_e32 v108, v0
	v_mov_b32_e32 v109, v0
	v_mov_b32_e32 v110, v0
	v_mov_b32_e32 v111, v0
	v_mov_b32_e32 v112, v0
	v_mov_b32_e32 v113, v0
	v_mov_b32_e32 v114, v0
	v_mov_b32_e32 v115, v0
	v_mov_b32_e32 v116, v0
	v_mov_b32_e32 v117, v0
	v_mov_b32_e32 v118, v0
	v_mov_b32_e32 v119, v0
	v_mov_b32_e32 v120, v0
	v_mov_b32_e32 v121, v0
	v_mov_b32_e32 v122, v0
	v_mov_b32_e32 v123, v0
	v_mov_b32_e32 v124, v0
	v_mov_b32_e32 v125, v0
	v_mov_b32_e32 v126, v0
	v_mov_b32_e32 v127, v0
	v_mov_b32_e32 v135, v134
	v_mov_b32_e32 v136, v134
	v_mov_b32_e32 v137, v134
	v_mov_b32_e32 v138, v134
	v_mov_b32_e32 v139, v134
	v_mov_b32_e32 v140, v134
	v_mov_b32_e32 v141, v134
	v_mov_b32_e32 v146, v134
	v_mov_b32_e32 v147, v134
	v_mov_b32_e32 v148, v134
	v_mov_b32_e32 v149, v134
	v_mov_b32_e32 v150, v134
	v_mov_b32_e32 v151, v134
	v_mov_b32_e32 v152, v134
	v_mov_b32_e32 v153, v134
	v_mov_b32_e32 v131, v130
	v_mov_b32_e32 v132, v130
	v_mov_b32_e32 v133, v130
	v_mov_b32_e32 v142, v130
	v_mov_b32_e32 v143, v130
	v_mov_b32_e32 v144, v130
	v_mov_b32_e32 v145, v130

.LBB0_2225:
	s_and_b32 s6, s2, 7
	v_lshl_add_u32 v0, s6, 8, v201
	v_ashrrev_i32_e32 v1, 31, v0
	v_lshlrev_b64 v[0:1], 12, v[0:1]
	s_and_b32 s6, s5, 0xffffff00
	v_lshl_add_u64 v[170:171], v[160:161], 0, v[0:1]
	v_add_u32_e32 v0, s6, v175
	s_and_b32 s6, s4, 7
	v_ashrrev_i32_e32 v1, 31, v0
	s_or_b32 s6, s6, s3
	v_lshlrev_b64 v[0:1], 12, v[0:1]
	s_lshl_b32 s6, s6, 8
	v_lshl_add_u64 v[172:173], v[168:169], 0, v[0:1]
	v_add_u32_e32 v0, s6, v175
	s_lshl_b32 s7, s4, 5
	v_ashrrev_i32_e32 v1, 31, v0
	s_and_b32 s7, s7, 0xffffff00
	v_add_u32_e32 v2, s7, v175
	v_lshlrev_b64 v[0:1], 12, v[0:1]
	s_waitcnt lgkmcnt(0)
	s_barrier
	v_and_b32_e32 v238, 0xff, v163
	v_add_u32_e32 v239, s6, v238
	v_lshlrev_b32_e32 v239, 2, v239
	global_load_dword v239, v239, s[0:1]
	v_lshlrev_b32_e32 v238, 2, v238
	v_add_u32_e32 v238, 0x20020, v238
	v_mov_b32_e32 v250, 0x20020
	v_ashrrev_i32_e32 v3, 31, v2
	v_lshl_add_u64 v[0:1], v[154:155], 0, v[0:1]
	v_readfirstlane_b32 s8, v180
	s_mov_b32 m0, s8
	s_nop 0
	global_load_lds_dwordx4 v[0:1], off
	s_mov_b64 s[12:13], 0x80000
	v_lshlrev_b64 v[2:3], 12, v[2:3]
	v_lshl_add_u64 v[4:5], v[0:1], 0, s[12:13]
	s_add_i32 s9, s8, 0x2000
	s_mov_b32 m0, s9
	s_nop 0
	global_load_lds_dwordx4 v[4:5], off
	v_lshl_add_u64 v[2:3], v[156:157], 0, v[2:3]
	s_add_i32 s9, s8, 0x4000
	s_mov_b32 m0, s9
	s_nop 0
	global_load_lds_dwordx4 v[2:3], off
	v_lshl_add_u64 v[4:5], v[2:3], 0, s[12:13]
	s_add_i32 s9, s8, 0x6000
	s_mov_b32 m0, s9
	s_nop 0
	global_load_lds_dwordx4 v[4:5], off
	s_add_i32 s9, s8, 0x8000
	v_lshl_add_u64 v[4:5], v[0:1], 0, 64
	s_mov_b32 m0, s9
	s_nop 0
	global_load_lds_dwordx4 v[4:5], off
	s_mov_b64 s[10:11], 0x80040
	v_lshl_add_u64 v[4:5], v[0:1], 0, s[10:11]
	s_add_i32 s9, s8, 0xa000
	s_mov_b32 m0, s9
	s_nop 0
	global_load_lds_dwordx4 v[4:5], off
	v_lshl_add_u64 v[4:5], v[2:3], 0, 64
	s_add_i32 s9, s8, 0xc000
	s_mov_b32 m0, s9
	s_nop 0
	global_load_lds_dwordx4 v[4:5], off
	v_lshl_add_u64 v[4:5], v[2:3], 0, s[10:11]
	s_add_i32 s9, s8, 0xe000
	s_mov_b32 m0, s9
	s_nop 0
	global_load_lds_dwordx4 v[4:5], off
	s_mov_b64 s[10:11], 0x80
	s_add_i32 s9, s8, 0x10000
	v_lshl_add_u64 v[4:5], v[0:1], 0, s[10:11]
	s_mov_b32 m0, s9
	s_nop 0
	global_load_lds_dwordx4 v[4:5], off
	s_mov_b64 s[14:15], 0x80080
	v_lshl_add_u64 v[0:1], v[0:1], 0, s[14:15]
	s_add_i32 s9, s8, 0x12000
	s_mov_b32 m0, s9
	s_nop 0
	global_load_lds_dwordx4 v[0:1], off
	v_lshl_add_u64 v[0:1], v[2:3], 0, s[10:11]
	s_add_i32 s9, s8, 0x14000
	s_mov_b32 m0, s9
	s_nop 0
	global_load_lds_dwordx4 v[0:1], off
	v_lshl_add_u64 v[0:1], v[2:3], 0, s[14:15]
	s_add_i32 s8, s8, 0x16000
	s_mov_b32 m0, s8
	s_nop 0
	global_load_lds_dwordx4 v[0:1], off
	s_waitcnt vmcnt(12)
	ds_write_b32 v238, v239
	v_mov_b32_e32 v130, 0
	v_mov_b32_e32 v134, 0
	v_mov_b32_e32 v0, 0
	s_mov_b32 s8, 0x18000
	v_mov_b32_e32 v1, v0
	v_mov_b32_e32 v2, v0
	v_mov_b32_e32 v3, v0
	v_mov_b32_e32 v4, v0
	v_mov_b32_e32 v5, v0
	v_mov_b32_e32 v6, v0
	v_mov_b32_e32 v7, v0
	v_mov_b32_e32 v8, v0
	v_mov_b32_e32 v9, v0
	v_mov_b32_e32 v10, v0
	v_mov_b32_e32 v11, v0
	v_mov_b32_e32 v12, v0
	v_mov_b32_e32 v13, v0
	v_mov_b32_e32 v14, v0
	v_mov_b32_e32 v15, v0
	v_mov_b32_e32 v16, v0
	v_mov_b32_e32 v17, v0
	v_mov_b32_e32 v18, v0
	v_mov_b32_e32 v19, v0
	v_mov_b32_e32 v20, v0
	v_mov_b32_e32 v21, v0
	v_mov_b32_e32 v22, v0
	v_mov_b32_e32 v23, v0
	v_mov_b32_e32 v24, v0
	v_mov_b32_e32 v25, v0
	v_mov_b32_e32 v26, v0
	v_mov_b32_e32 v27, v0
	v_mov_b32_e32 v28, v0
	v_mov_b32_e32 v29, v0
	v_mov_b32_e32 v30, v0
	v_mov_b32_e32 v31, v0
	v_mov_b32_e32 v32, v0
	v_mov_b32_e32 v33, v0
	v_mov_b32_e32 v34, v0
	v_mov_b32_e32 v35, v0
	v_mov_b32_e32 v36, v0
	v_mov_b32_e32 v37, v0
	v_mov_b32_e32 v38, v0
	v_mov_b32_e32 v39, v0
	v_mov_b32_e32 v40, v0
	v_mov_b32_e32 v41, v0
	v_mov_b32_e32 v42, v0
	v_mov_b32_e32 v43, v0
	v_mov_b32_e32 v44, v0
	v_mov_b32_e32 v45, v0
	v_mov_b32_e32 v46, v0
	v_mov_b32_e32 v47, v0
	v_mov_b32_e32 v48, v0
	v_mov_b32_e32 v49, v0
	v_mov_b32_e32 v50, v0
	v_mov_b32_e32 v51, v0
	v_mov_b32_e32 v52, v0
	v_mov_b32_e32 v53, v0
	v_mov_b32_e32 v54, v0
	v_mov_b32_e32 v55, v0
	v_mov_b32_e32 v56, v0
	v_mov_b32_e32 v57, v0
	v_mov_b32_e32 v58, v0
	v_mov_b32_e32 v59, v0
	v_mov_b32_e32 v60, v0
	v_mov_b32_e32 v61, v0
	v_mov_b32_e32 v62, v0
	v_mov_b32_e32 v63, v0
	v_mov_b32_e32 v64, v0
	v_mov_b32_e32 v65, v0
	v_mov_b32_e32 v66, v0
	v_mov_b32_e32 v67, v0
	v_mov_b32_e32 v68, v0
	v_mov_b32_e32 v69, v0
	v_mov_b32_e32 v70, v0
	v_mov_b32_e32 v71, v0
	v_mov_b32_e32 v72, v0
	v_mov_b32_e32 v73, v0
	v_mov_b32_e32 v74, v0
	v_mov_b32_e32 v75, v0
	v_mov_b32_e32 v76, v0
	v_mov_b32_e32 v77, v0
	v_mov_b32_e32 v78, v0
	v_mov_b32_e32 v79, v0
	v_mov_b32_e32 v80, v0
	v_mov_b32_e32 v81, v0
	v_mov_b32_e32 v82, v0
	v_mov_b32_e32 v83, v0
	v_mov_b32_e32 v84, v0
	v_mov_b32_e32 v85, v0
	v_mov_b32_e32 v86, v0
	v_mov_b32_e32 v87, v0
	v_mov_b32_e32 v88, v0
	v_mov_b32_e32 v89, v0
	v_mov_b32_e32 v90, v0
	v_mov_b32_e32 v91, v0
	v_mov_b32_e32 v92, v0
	v_mov_b32_e32 v93, v0
	v_mov_b32_e32 v94, v0
	v_mov_b32_e32 v95, v0
	v_mov_b32_e32 v96, v0
	v_mov_b32_e32 v97, v0
	v_mov_b32_e32 v98, v0
	v_mov_b32_e32 v99, v0
	v_mov_b32_e32 v100, v0
	v_mov_b32_e32 v101, v0
	v_mov_b32_e32 v102, v0
	v_mov_b32_e32 v103, v0
	v_mov_b32_e32 v104, v0
	v_mov_b32_e32 v105, v0
	v_mov_b32_e32 v106, v0
	v_mov_b32_e32 v107, v0
	v_mov_b32_e32 v108, v0
	v_mov_b32_e32 v109, v0
	v_mov_b32_e32 v110, v0
	v_mov_b32_e32 v111, v0
	v_mov_b32_e32 v112, v0
	v_mov_b32_e32 v113, v0
	v_mov_b32_e32 v114, v0
	v_mov_b32_e32 v115, v0
	v_mov_b32_e32 v116, v0
	v_mov_b32_e32 v117, v0
	v_mov_b32_e32 v118, v0
	v_mov_b32_e32 v119, v0
	v_mov_b32_e32 v120, v0
	v_mov_b32_e32 v121, v0
	v_mov_b32_e32 v122, v0
	v_mov_b32_e32 v123, v0
	v_mov_b32_e32 v124, v0
	v_mov_b32_e32 v125, v0
	v_mov_b32_e32 v126, v0
	v_mov_b32_e32 v127, v0
	v_mov_b32_e32 v135, v134
	v_mov_b32_e32 v136, v134
	v_mov_b32_e32 v137, v134
	v_mov_b32_e32 v138, v134
	v_mov_b32_e32 v139, v134
	v_mov_b32_e32 v140, v134
	v_mov_b32_e32 v141, v134
	v_mov_b32_e32 v146, v134
	v_mov_b32_e32 v147, v134
	v_mov_b32_e32 v148, v134
	v_mov_b32_e32 v149, v134
	v_mov_b32_e32 v150, v134
	v_mov_b32_e32 v151, v134
	v_mov_b32_e32 v152, v134
	v_mov_b32_e32 v153, v134
	v_mov_b32_e32 v131, v130
	v_mov_b32_e32 v132, v130
	v_mov_b32_e32 v133, v130
	v_mov_b32_e32 v142, v130
	v_mov_b32_e32 v143, v130
	v_mov_b32_e32 v144, v130
	v_mov_b32_e32 v145, v130

.LBB0_2339:
	s_and_b32 s12, s15, 7
	v_lshl_add_u32 v0, s12, 8, v186
	v_ashrrev_i32_e32 v1, 31, v0
	v_lshlrev_b64 v[0:1], 11, v[0:1]
	s_and_b32 s12, s17, 0xffffff00
	v_lshl_add_u64 v[170:171], v[160:161], 0, v[0:1]
	v_add_u32_e32 v0, s12, v175
	s_and_b32 s12, s14, 7
	v_ashrrev_i32_e32 v1, 31, v0
	s_or_b32 s12, s12, s16
	v_lshlrev_b64 v[0:1], 11, v[0:1]
	s_lshl_b32 s13, s12, 8
	v_lshl_add_u64 v[172:173], v[168:169], 0, v[0:1]
	v_add_u32_e32 v0, s13, v175
	s_lshl_b32 s12, s14, 5
	v_ashrrev_i32_e32 v1, 31, v0
	s_and_b32 s12, s12, 0xffffff00
	v_lshlrev_b64 v[0:1], 11, v[0:1]
	v_add_u32_e32 v2, s12, v175
	s_waitcnt lgkmcnt(0)
	s_barrier
	v_ashrrev_i32_e32 v3, 31, v2
	v_lshl_add_u64 v[0:1], v[156:157], 0, v[0:1]
	v_readfirstlane_b32 s18, v180
	s_mov_b32 m0, s18
	s_nop 0
	global_load_lds_dwordx4 v[0:1], off
	v_lshlrev_b64 v[2:3], 11, v[2:3]
	v_lshl_add_u64 v[4:5], v[0:1], 0, s[34:35]
	s_add_i32 s19, s18, 0x2000
	s_mov_b32 m0, s19
	s_nop 0
	global_load_lds_dwordx4 v[4:5], off
	v_lshl_add_u64 v[2:3], v[158:159], 0, v[2:3]
	s_add_i32 s19, s18, 0x4000
	s_mov_b32 m0, s19
	s_nop 0
	global_load_lds_dwordx4 v[2:3], off
	v_lshl_add_u64 v[4:5], v[2:3], 0, s[34:35]
	s_add_i32 s19, s18, 0x6000
	s_mov_b32 m0, s19
	s_nop 0
	global_load_lds_dwordx4 v[4:5], off
	s_add_i32 s19, s18, 0x8000
	v_lshl_add_u64 v[4:5], v[0:1], 0, 64
	s_mov_b32 m0, s19
	s_nop 0
	global_load_lds_dwordx4 v[4:5], off
	s_mov_b64 s[20:21], 0x40040
	v_lshl_add_u64 v[4:5], v[0:1], 0, s[20:21]
	s_add_i32 s19, s18, 0xa000
	s_mov_b32 m0, s19
	s_nop 0
	global_load_lds_dwordx4 v[4:5], off
	v_lshl_add_u64 v[4:5], v[2:3], 0, 64
	s_add_i32 s19, s18, 0xc000
	s_mov_b32 m0, s19
	s_nop 0
	global_load_lds_dwordx4 v[4:5], off
	v_lshl_add_u64 v[4:5], v[2:3], 0, s[20:21]
	s_add_i32 s19, s18, 0xe000
	s_mov_b32 m0, s19
	s_nop 0
	global_load_lds_dwordx4 v[4:5], off
	s_mov_b64 s[20:21], 0x80
	s_add_i32 s19, s18, 0x10000
	v_lshl_add_u64 v[4:5], v[0:1], 0, s[20:21]
	s_mov_b32 m0, s19
	s_nop 0
	global_load_lds_dwordx4 v[4:5], off
	s_mov_b64 s[22:23], 0x40080
	v_lshl_add_u64 v[0:1], v[0:1], 0, s[22:23]
	s_add_i32 s19, s18, 0x12000
	s_mov_b32 m0, s19
	s_nop 0
	global_load_lds_dwordx4 v[0:1], off
	v_lshl_add_u64 v[0:1], v[2:3], 0, s[20:21]
	s_add_i32 s19, s18, 0x14000
	s_mov_b32 m0, s19
	s_nop 0
	global_load_lds_dwordx4 v[0:1], off
	v_lshl_add_u64 v[0:1], v[2:3], 0, s[22:23]
	s_add_i32 s18, s18, 0x16000
	s_mov_b32 m0, s18
	s_nop 0
	global_load_lds_dwordx4 v[0:1], off
	v_mov_b32_e32 v130, 0
	v_mov_b32_e32 v134, 0
	v_mov_b32_e32 v0, 0
	s_mov_b32 s18, 0x18000
	v_mov_b32_e32 v1, v0
	v_mov_b32_e32 v2, v0
	v_mov_b32_e32 v3, v0
	v_mov_b32_e32 v4, v0
	v_mov_b32_e32 v5, v0
	v_mov_b32_e32 v6, v0
	v_mov_b32_e32 v7, v0
	v_mov_b32_e32 v8, v0
	v_mov_b32_e32 v9, v0
	v_mov_b32_e32 v10, v0
	v_mov_b32_e32 v11, v0
	v_mov_b32_e32 v12, v0
	v_mov_b32_e32 v13, v0
	v_mov_b32_e32 v14, v0
	v_mov_b32_e32 v15, v0
	v_mov_b32_e32 v16, v0
	v_mov_b32_e32 v17, v0
	v_mov_b32_e32 v18, v0
	v_mov_b32_e32 v19, v0
	v_mov_b32_e32 v20, v0
	v_mov_b32_e32 v21, v0
	v_mov_b32_e32 v22, v0
	v_mov_b32_e32 v23, v0
	v_mov_b32_e32 v24, v0
	v_mov_b32_e32 v25, v0
	v_mov_b32_e32 v26, v0
	v_mov_b32_e32 v27, v0
	v_mov_b32_e32 v28, v0
	v_mov_b32_e32 v29, v0
	v_mov_b32_e32 v30, v0
	v_mov_b32_e32 v31, v0
	v_mov_b32_e32 v32, v0
	v_mov_b32_e32 v33, v0
	v_mov_b32_e32 v34, v0
	v_mov_b32_e32 v35, v0
	v_mov_b32_e32 v36, v0
	v_mov_b32_e32 v37, v0
	v_mov_b32_e32 v38, v0
	v_mov_b32_e32 v39, v0
	v_mov_b32_e32 v40, v0
	v_mov_b32_e32 v41, v0
	v_mov_b32_e32 v42, v0
	v_mov_b32_e32 v43, v0
	v_mov_b32_e32 v44, v0
	v_mov_b32_e32 v45, v0
	v_mov_b32_e32 v46, v0
	v_mov_b32_e32 v47, v0
	v_mov_b32_e32 v48, v0
	v_mov_b32_e32 v49, v0
	v_mov_b32_e32 v50, v0
	v_mov_b32_e32 v51, v0
	v_mov_b32_e32 v52, v0
	v_mov_b32_e32 v53, v0
	v_mov_b32_e32 v54, v0
	v_mov_b32_e32 v55, v0
	v_mov_b32_e32 v56, v0
	v_mov_b32_e32 v57, v0
	v_mov_b32_e32 v58, v0
	v_mov_b32_e32 v59, v0
	v_mov_b32_e32 v60, v0
	v_mov_b32_e32 v61, v0
	v_mov_b32_e32 v62, v0
	v_mov_b32_e32 v63, v0
	v_mov_b32_e32 v64, v0
	v_mov_b32_e32 v65, v0
	v_mov_b32_e32 v66, v0
	v_mov_b32_e32 v67, v0
	v_mov_b32_e32 v68, v0
	v_mov_b32_e32 v69, v0
	v_mov_b32_e32 v70, v0
	v_mov_b32_e32 v71, v0
	v_mov_b32_e32 v72, v0
	v_mov_b32_e32 v73, v0
	v_mov_b32_e32 v74, v0
	v_mov_b32_e32 v75, v0
	v_mov_b32_e32 v76, v0
	v_mov_b32_e32 v77, v0
	v_mov_b32_e32 v78, v0
	v_mov_b32_e32 v79, v0
	v_mov_b32_e32 v80, v0
	v_mov_b32_e32 v81, v0
	v_mov_b32_e32 v82, v0
	v_mov_b32_e32 v83, v0
	v_mov_b32_e32 v84, v0
	v_mov_b32_e32 v85, v0
	v_mov_b32_e32 v86, v0
	v_mov_b32_e32 v87, v0
	v_mov_b32_e32 v88, v0
	v_mov_b32_e32 v89, v0
	v_mov_b32_e32 v90, v0
	v_mov_b32_e32 v91, v0
	v_mov_b32_e32 v92, v0
	v_mov_b32_e32 v93, v0
	v_mov_b32_e32 v94, v0
	v_mov_b32_e32 v95, v0
	v_mov_b32_e32 v96, v0
	v_mov_b32_e32 v97, v0
	v_mov_b32_e32 v98, v0
	v_mov_b32_e32 v99, v0
	v_mov_b32_e32 v100, v0
	v_mov_b32_e32 v101, v0
	v_mov_b32_e32 v102, v0
	v_mov_b32_e32 v103, v0
	v_mov_b32_e32 v104, v0
	v_mov_b32_e32 v105, v0
	v_mov_b32_e32 v106, v0
	v_mov_b32_e32 v107, v0
	v_mov_b32_e32 v108, v0
	v_mov_b32_e32 v109, v0
	v_mov_b32_e32 v110, v0
	v_mov_b32_e32 v111, v0
	v_mov_b32_e32 v112, v0
	v_mov_b32_e32 v113, v0
	v_mov_b32_e32 v114, v0
	v_mov_b32_e32 v115, v0
	v_mov_b32_e32 v116, v0
	v_mov_b32_e32 v117, v0
	v_mov_b32_e32 v118, v0
	v_mov_b32_e32 v119, v0
	v_mov_b32_e32 v120, v0
	v_mov_b32_e32 v121, v0
	v_mov_b32_e32 v122, v0
	v_mov_b32_e32 v123, v0
	v_mov_b32_e32 v124, v0
	v_mov_b32_e32 v125, v0
	v_mov_b32_e32 v126, v0
	v_mov_b32_e32 v127, v0
	v_mov_b32_e32 v135, v134
	v_mov_b32_e32 v136, v134
	v_mov_b32_e32 v137, v134
	v_mov_b32_e32 v138, v134
	v_mov_b32_e32 v139, v134
	v_mov_b32_e32 v140, v134
	v_mov_b32_e32 v141, v134
	v_mov_b32_e32 v146, v134
	v_mov_b32_e32 v147, v134
	v_mov_b32_e32 v148, v134
	v_mov_b32_e32 v149, v134
	v_mov_b32_e32 v150, v134
	v_mov_b32_e32 v151, v134
	v_mov_b32_e32 v152, v134
	v_mov_b32_e32 v153, v134
	v_mov_b32_e32 v131, v130
	v_mov_b32_e32 v132, v130
	v_mov_b32_e32 v133, v130
	v_mov_b32_e32 v142, v130
	v_mov_b32_e32 v143, v130
	v_mov_b32_e32 v144, v130
	v_mov_b32_e32 v145, v130

.LBB0_2550:
	s_and_b32 s3, s0, 7
	v_lshl_add_u32 v0, s3, 8, v201
	s_and_b32 s3, s2, 0xffffff00
	v_mad_i64_i32 v[170:171], s[4:5], v0, s7, v[160:161]
	v_add_u32_e32 v0, s3, v175
	s_and_b32 s3, s6, 7
	v_mad_i64_i32 v[172:173], s[4:5], v0, s7, v[168:169]
	s_or_b32 s3, s3, s1
	s_lshl_b32 s3, s3, 8
	s_lshl_b32 s4, s6, 5
	v_add_u32_e32 v0, s3, v175
	s_and_b32 s4, s4, 0xffffff00
	s_waitcnt lgkmcnt(0)
	s_barrier
	v_add_u32_e32 v2, s4, v175
	v_mad_i64_i32 v[0:1], s[8:9], v0, s7, v[154:155]
	v_readfirstlane_b32 s5, v180
	s_mov_b32 m0, s5
	s_nop 0
	global_load_lds_dwordx4 v[0:1], off
	v_mad_i64_i32 v[2:3], s[8:9], v2, s7, v[156:157]
	v_lshl_add_u64 v[4:5], v[0:1], 0, s[10:11]
	s_add_i32 s7, s5, 0x2000
	s_mov_b32 m0, s7
	s_nop 0
	global_load_lds_dwordx4 v[4:5], off
	s_add_i32 s7, s5, 0x4000
	s_mov_b32 m0, s7
	s_nop 0
	global_load_lds_dwordx4 v[2:3], off
	v_lshl_add_u64 v[4:5], v[2:3], 0, s[10:11]
	s_add_i32 s7, s5, 0x6000
	s_mov_b32 m0, s7
	s_nop 0
	global_load_lds_dwordx4 v[4:5], off
	s_add_i32 s7, s5, 0x8000
	v_lshl_add_u64 v[4:5], v[0:1], 0, 64
	s_mov_b32 m0, s7
	s_nop 0
	global_load_lds_dwordx4 v[4:5], off
	s_mov_b64 s[8:9], 0xb0040
	v_lshl_add_u64 v[4:5], v[0:1], 0, s[8:9]
	s_add_i32 s7, s5, 0xa000
	s_mov_b32 m0, s7
	s_nop 0
	global_load_lds_dwordx4 v[4:5], off
	v_lshl_add_u64 v[4:5], v[2:3], 0, 64
	s_add_i32 s7, s5, 0xc000
	s_mov_b32 m0, s7
	s_nop 0
	global_load_lds_dwordx4 v[4:5], off
	v_lshl_add_u64 v[4:5], v[2:3], 0, s[8:9]
	s_add_i32 s7, s5, 0xe000
	s_mov_b32 m0, s7
	s_nop 0
	global_load_lds_dwordx4 v[4:5], off
	s_mov_b64 s[8:9], 0x80
	s_add_i32 s7, s5, 0x10000
	v_lshl_add_u64 v[4:5], v[0:1], 0, s[8:9]
	s_mov_b32 m0, s7
	s_nop 0
	global_load_lds_dwordx4 v[4:5], off
	s_mov_b64 s[12:13], 0xb0080
	v_lshl_add_u64 v[0:1], v[0:1], 0, s[12:13]
	s_add_i32 s7, s5, 0x12000
	s_mov_b32 m0, s7
	s_nop 0
	global_load_lds_dwordx4 v[0:1], off
	v_lshl_add_u64 v[0:1], v[2:3], 0, s[8:9]
	s_add_i32 s7, s5, 0x14000
	s_mov_b32 m0, s7
	s_nop 0
	global_load_lds_dwordx4 v[0:1], off
	v_lshl_add_u64 v[0:1], v[2:3], 0, s[12:13]
	s_add_i32 s5, s5, 0x16000
	s_mov_b32 m0, s5
	s_nop 0
	global_load_lds_dwordx4 v[0:1], off
	v_mov_b32_e32 v130, 0
	v_mov_b32_e32 v134, 0
	v_mov_b32_e32 v0, 0
	s_mov_b32 s5, 0x18000
	v_mov_b32_e32 v1, v0
	v_mov_b32_e32 v2, v0
	v_mov_b32_e32 v3, v0
	v_mov_b32_e32 v4, v0
	v_mov_b32_e32 v5, v0
	v_mov_b32_e32 v6, v0
	v_mov_b32_e32 v7, v0
	v_mov_b32_e32 v8, v0
	v_mov_b32_e32 v9, v0
	v_mov_b32_e32 v10, v0
	v_mov_b32_e32 v11, v0
	v_mov_b32_e32 v12, v0
	v_mov_b32_e32 v13, v0
	v_mov_b32_e32 v14, v0
	v_mov_b32_e32 v15, v0
	v_mov_b32_e32 v16, v0
	v_mov_b32_e32 v17, v0
	v_mov_b32_e32 v18, v0
	v_mov_b32_e32 v19, v0
	v_mov_b32_e32 v20, v0
	v_mov_b32_e32 v21, v0
	v_mov_b32_e32 v22, v0
	v_mov_b32_e32 v23, v0
	v_mov_b32_e32 v24, v0
	v_mov_b32_e32 v25, v0
	v_mov_b32_e32 v26, v0
	v_mov_b32_e32 v27, v0
	v_mov_b32_e32 v28, v0
	v_mov_b32_e32 v29, v0
	v_mov_b32_e32 v30, v0
	v_mov_b32_e32 v31, v0
	v_mov_b32_e32 v32, v0
	v_mov_b32_e32 v33, v0
	v_mov_b32_e32 v34, v0
	v_mov_b32_e32 v35, v0
	v_mov_b32_e32 v36, v0
	v_mov_b32_e32 v37, v0
	v_mov_b32_e32 v38, v0
	v_mov_b32_e32 v39, v0
	v_mov_b32_e32 v40, v0
	v_mov_b32_e32 v41, v0
	v_mov_b32_e32 v42, v0
	v_mov_b32_e32 v43, v0
	v_mov_b32_e32 v44, v0
	v_mov_b32_e32 v45, v0
	v_mov_b32_e32 v46, v0
	v_mov_b32_e32 v47, v0
	v_mov_b32_e32 v48, v0
	v_mov_b32_e32 v49, v0
	v_mov_b32_e32 v50, v0
	v_mov_b32_e32 v51, v0
	v_mov_b32_e32 v52, v0
	v_mov_b32_e32 v53, v0
	v_mov_b32_e32 v54, v0
	v_mov_b32_e32 v55, v0
	v_mov_b32_e32 v56, v0
	v_mov_b32_e32 v57, v0
	v_mov_b32_e32 v58, v0
	v_mov_b32_e32 v59, v0
	v_mov_b32_e32 v60, v0
	v_mov_b32_e32 v61, v0
	v_mov_b32_e32 v62, v0
	v_mov_b32_e32 v63, v0
	v_mov_b32_e32 v64, v0
	v_mov_b32_e32 v65, v0
	v_mov_b32_e32 v66, v0
	v_mov_b32_e32 v67, v0
	v_mov_b32_e32 v68, v0
	v_mov_b32_e32 v69, v0
	v_mov_b32_e32 v70, v0
	v_mov_b32_e32 v71, v0
	v_mov_b32_e32 v72, v0
	v_mov_b32_e32 v73, v0
	v_mov_b32_e32 v74, v0
	v_mov_b32_e32 v75, v0
	v_mov_b32_e32 v76, v0
	v_mov_b32_e32 v77, v0
	v_mov_b32_e32 v78, v0
	v_mov_b32_e32 v79, v0
	v_mov_b32_e32 v80, v0
	v_mov_b32_e32 v81, v0
	v_mov_b32_e32 v82, v0
	v_mov_b32_e32 v83, v0
	v_mov_b32_e32 v84, v0
	v_mov_b32_e32 v85, v0
	v_mov_b32_e32 v86, v0
	v_mov_b32_e32 v87, v0
	v_mov_b32_e32 v88, v0
	v_mov_b32_e32 v89, v0
	v_mov_b32_e32 v90, v0
	v_mov_b32_e32 v91, v0
	v_mov_b32_e32 v92, v0
	v_mov_b32_e32 v93, v0
	v_mov_b32_e32 v94, v0
	v_mov_b32_e32 v95, v0
	v_mov_b32_e32 v96, v0
	v_mov_b32_e32 v97, v0
	v_mov_b32_e32 v98, v0
	v_mov_b32_e32 v99, v0
	v_mov_b32_e32 v100, v0
	v_mov_b32_e32 v101, v0
	v_mov_b32_e32 v102, v0
	v_mov_b32_e32 v103, v0
	v_mov_b32_e32 v104, v0
	v_mov_b32_e32 v105, v0
	v_mov_b32_e32 v106, v0
	v_mov_b32_e32 v107, v0
	v_mov_b32_e32 v108, v0
	v_mov_b32_e32 v109, v0
	v_mov_b32_e32 v110, v0
	v_mov_b32_e32 v111, v0
	v_mov_b32_e32 v112, v0
	v_mov_b32_e32 v113, v0
	v_mov_b32_e32 v114, v0
	v_mov_b32_e32 v115, v0
	v_mov_b32_e32 v116, v0
	v_mov_b32_e32 v117, v0
	v_mov_b32_e32 v118, v0
	v_mov_b32_e32 v119, v0
	v_mov_b32_e32 v120, v0
	v_mov_b32_e32 v121, v0
	v_mov_b32_e32 v122, v0
	v_mov_b32_e32 v123, v0
	v_mov_b32_e32 v124, v0
	v_mov_b32_e32 v125, v0
	v_mov_b32_e32 v126, v0
	v_mov_b32_e32 v127, v0
	v_mov_b32_e32 v135, v134
	v_mov_b32_e32 v136, v134
	v_mov_b32_e32 v137, v134
	v_mov_b32_e32 v138, v134
	v_mov_b32_e32 v139, v134
	v_mov_b32_e32 v140, v134
	v_mov_b32_e32 v141, v134
	v_mov_b32_e32 v146, v134
	v_mov_b32_e32 v147, v134
	v_mov_b32_e32 v148, v134
	v_mov_b32_e32 v149, v134
	v_mov_b32_e32 v150, v134
	v_mov_b32_e32 v151, v134
	v_mov_b32_e32 v152, v134
	v_mov_b32_e32 v153, v134
	v_mov_b32_e32 v131, v130
	v_mov_b32_e32 v132, v130
	v_mov_b32_e32 v133, v130
	v_mov_b32_e32 v142, v130
	v_mov_b32_e32 v143, v130
	v_mov_b32_e32 v144, v130
	v_mov_b32_e32 v145, v130
